# banded attention: ALiBi bias / window-mask blocks rewritten (2 resp. 4 VALU per score instead of 3 resp. 6, bit-identical)
# baseline (speedup 1.0000x reference)
.LBB0_904:
	s_waitcnt vmcnt(0)
	v_mfma_f32_32x32x16_bf16 v[66:81], v[142:145], v[98:101], 0
	s_mov_b32 s10, s52
	s_add_i32 s52, s52, 1
	s_cmp_ge_u32 s52, s51
	v_lshl_add_u64 v[0:1], v[206:207], 0, s[40:41]
	s_cselect_b64 s[42:43], -1, 0
	s_cmp_lt_u32 s52, s51
	global_load_dwordx4 v[174:177], v[0:1], off
	global_load_dwordx4 v[170:173], v[0:1], off offset:1024
	global_load_dwordx4 v[166:169], v[0:1], off offset:2048
	global_load_dwordx4 v[162:165], v[0:1], off offset:3072
	v_mfma_f32_32x32x16_bf16 v[82:97], v[126:129], v[98:101], 0
	v_add_co_u32_e32 v0, vcc, s79, v0
	s_cselect_b32 s16, s52, s10
	s_nop 0
	v_addc_co_u32_e32 v1, vcc, 0, v1, vcc
	s_lshl_b64 s[40:41], s[16:17], 13
	global_load_dwordx4 v[158:161], v[0:1], off
	global_load_dwordx4 v[154:157], v[0:1], off offset:1024
	global_load_dwordx4 v[150:153], v[0:1], off offset:2048
	global_load_dwordx4 v[146:149], v[0:1], off offset:3072
	v_mfma_f32_32x32x16_bf16 v[66:81], v[138:141], v[102:105], v[66:81]
	v_lshl_add_u64 v[0:1], v[204:205], 0, s[40:41]
	global_load_dwordx4 v[142:145], v[0:1], off
	global_load_dwordx4 v[138:141], v[0:1], off offset:1024
	s_cmp_lt_u32 s9, s53
	s_cselect_b64 s[10:11], -1, 0
	s_cmp_gt_i32 s9, s54
	s_cselect_b64 s[44:45], -1, 0
	s_and_b64 s[10:11], s[10:11], s[44:45]
	v_mfma_f32_32x32x16_bf16 v[82:97], v[122:125], v[102:105], v[82:97]
	s_mov_b64 s[44:45], -1
	v_mfma_f32_32x32x16_bf16 v[66:81], v[134:137], v[106:109], v[66:81]
	v_mfma_f32_32x32x16_bf16 v[82:97], v[118:121], v[106:109], v[82:97]
	v_mfma_f32_32x32x16_bf16 v[66:81], v[130:133], v[110:113], v[66:81]
	global_load_dwordx4 v[134:137], v[0:1], off offset:2048
	global_load_dwordx4 v[130:133], v[0:1], off offset:3072
	v_add_co_u32_e32 v0, vcc, s79, v0
	s_nop 1
	v_addc_co_u32_e32 v1, vcc, 0, v1, vcc
	global_load_dwordx4 v[126:129], v[0:1], off
	global_load_dwordx4 v[122:125], v[0:1], off offset:1024
	v_mfma_f32_32x32x16_bf16 v[82:97], v[114:117], v[110:113], v[82:97]
	global_load_dwordx4 v[118:121], v[0:1], off offset:2048
	global_load_dwordx4 v[114:117], v[0:1], off offset:3072
	v_add_u32_e32 v0, s9, v212
	v_cvt_f32_i32_e32 v32, v0
	s_and_b64 vcc, exec, s[10:11]
	v_add_f32_e32 v215, 1.0, v32
	v_and_b32_e32 v208, 0x7fffffff, v32
	v_and_b32_e32 v209, 0x7fffffff, v215
	s_cbranch_vccnz .LBB0_906
	v_add_f32_e32 v1, 1.0, v32
	v_cmp_le_f32_e64 vcc, |v32|, s92
	v_cmp_le_f32_e64 s[10:11], |v1|, s92
	v_fma_f32 v0, s38, -|v32|, v66
	v_fma_f32 v1, s38, -|v1|, v67
	v_cndmask_b32_e32 v0, v242, v0, vcc
	v_cndmask_b32_e64 v1, v242, v1, s[10:11]
	v_add_f32_e32 v2, 2.0, v32
	v_add_f32_e32 v3, 0x40400000, v32
	v_cmp_le_f32_e64 vcc, |v2|, s92
	v_cmp_le_f32_e64 s[10:11], |v3|, s92
	v_fma_f32 v2, s38, -|v2|, v68
	v_fma_f32 v3, s38, -|v3|, v69
	v_cndmask_b32_e32 v2, v242, v2, vcc
	v_cndmask_b32_e64 v3, v242, v3, s[10:11]
	v_add_f32_e32 v4, 0x41000000, v32
	v_add_f32_e32 v5, 0x41100000, v32
	v_cmp_le_f32_e64 vcc, |v4|, s92
	v_cmp_le_f32_e64 s[10:11], |v5|, s92
	v_fma_f32 v4, s38, -|v4|, v70
	v_fma_f32 v5, s38, -|v5|, v71
	v_cndmask_b32_e32 v4, v242, v4, vcc
	v_cndmask_b32_e64 v5, v242, v5, s[10:11]
	v_add_f32_e32 v6, 0x41200000, v32
	v_add_f32_e32 v7, 0x41300000, v32
	v_cmp_le_f32_e64 vcc, |v6|, s92
	v_cmp_le_f32_e64 s[10:11], |v7|, s92
	v_fma_f32 v6, s38, -|v6|, v72
	v_fma_f32 v7, s38, -|v7|, v73
	v_cndmask_b32_e32 v6, v242, v6, vcc
	v_cndmask_b32_e64 v7, v242, v7, s[10:11]
	v_add_f32_e32 v8, 0x41800000, v32
	v_add_f32_e32 v9, 0x41880000, v32
	v_cmp_le_f32_e64 vcc, |v8|, s92
	v_cmp_le_f32_e64 s[10:11], |v9|, s92
	v_fma_f32 v8, s38, -|v8|, v74
	v_fma_f32 v9, s38, -|v9|, v75
	v_cndmask_b32_e32 v8, v242, v8, vcc
	v_cndmask_b32_e64 v9, v242, v9, s[10:11]
	v_add_f32_e32 v10, 0x41900000, v32
	v_add_f32_e32 v11, 0x41980000, v32
	v_cmp_le_f32_e64 vcc, |v10|, s92
	v_cmp_le_f32_e64 s[10:11], |v11|, s92
	v_fma_f32 v10, s38, -|v10|, v76
	v_fma_f32 v11, s38, -|v11|, v77
	v_cndmask_b32_e32 v10, v242, v10, vcc
	v_cndmask_b32_e64 v11, v242, v11, s[10:11]
	v_add_f32_e32 v12, 0x41c00000, v32
	v_add_f32_e32 v13, 0x41c80000, v32
	v_cmp_le_f32_e64 vcc, |v12|, s92
	v_cmp_le_f32_e64 s[10:11], |v13|, s92
	v_fma_f32 v12, s38, -|v12|, v78
	v_fma_f32 v13, s38, -|v13|, v79
	v_cndmask_b32_e32 v12, v242, v12, vcc
	v_cndmask_b32_e64 v13, v242, v13, s[10:11]
	v_add_f32_e32 v14, 0x41d00000, v32
	v_add_f32_e32 v15, 0x41d80000, v32
	v_cmp_le_f32_e64 vcc, |v14|, s92
	v_cmp_le_f32_e64 s[10:11], |v15|, s92
	v_fma_f32 v14, s38, -|v14|, v80
	v_fma_f32 v15, s38, -|v15|, v81
	v_cndmask_b32_e32 v14, v242, v14, vcc
	v_cndmask_b32_e64 v15, v242, v15, s[10:11]
	v_add_f32_e32 v16, 0x42000000, v32
	v_add_f32_e32 v17, 0x42040000, v32
	v_cmp_le_f32_e64 vcc, |v16|, s92
	v_cmp_le_f32_e64 s[10:11], |v17|, s92
	v_fma_f32 v16, s38, -|v16|, v82
	v_fma_f32 v17, s38, -|v17|, v83
	v_cndmask_b32_e32 v16, v242, v16, vcc
	v_cndmask_b32_e64 v17, v242, v17, s[10:11]
	v_add_f32_e32 v18, 0x42080000, v32
	v_add_f32_e32 v19, 0x420c0000, v32
	v_cmp_le_f32_e64 vcc, |v18|, s92
	v_cmp_le_f32_e64 s[10:11], |v19|, s92
	v_fma_f32 v18, s38, -|v18|, v84
	v_fma_f32 v19, s38, -|v19|, v85
	v_cndmask_b32_e32 v18, v242, v18, vcc
	v_cndmask_b32_e64 v19, v242, v19, s[10:11]
	v_add_f32_e32 v20, 0x42200000, v32
	v_add_f32_e32 v21, 0x42240000, v32
	v_cmp_le_f32_e64 vcc, |v20|, s92
	v_cmp_le_f32_e64 s[10:11], |v21|, s92
	v_fma_f32 v20, s38, -|v20|, v86
	v_fma_f32 v21, s38, -|v21|, v87
	v_cndmask_b32_e32 v20, v242, v20, vcc
	v_cndmask_b32_e64 v21, v242, v21, s[10:11]
	v_add_f32_e32 v22, 0x42280000, v32
	v_add_f32_e32 v23, 0x422c0000, v32
	v_cmp_le_f32_e64 vcc, |v22|, s92
	v_cmp_le_f32_e64 s[10:11], |v23|, s92
	v_fma_f32 v22, s38, -|v22|, v88
	v_fma_f32 v23, s38, -|v23|, v89
	v_cndmask_b32_e32 v22, v242, v22, vcc
	v_cndmask_b32_e64 v23, v242, v23, s[10:11]
	v_add_f32_e32 v24, 0x42400000, v32
	v_add_f32_e32 v25, 0x42440000, v32
	v_cmp_le_f32_e64 vcc, |v24|, s92
	v_cmp_le_f32_e64 s[10:11], |v25|, s92
	v_fma_f32 v24, s38, -|v24|, v90
	v_fma_f32 v25, s38, -|v25|, v91
	v_cndmask_b32_e32 v24, v242, v24, vcc
	v_cndmask_b32_e64 v25, v242, v25, s[10:11]
	v_add_f32_e32 v26, 0x42480000, v32
	v_add_f32_e32 v27, 0x424c0000, v32
	v_cmp_le_f32_e64 vcc, |v26|, s92
	v_cmp_le_f32_e64 s[10:11], |v27|, s92
	v_fma_f32 v26, s38, -|v26|, v92
	v_fma_f32 v27, s38, -|v27|, v93
	v_cndmask_b32_e32 v26, v242, v26, vcc
	v_cndmask_b32_e64 v27, v242, v27, s[10:11]
	v_add_f32_e32 v28, 0x42600000, v32
	v_add_f32_e32 v29, 0x42640000, v32
	v_cmp_le_f32_e64 vcc, |v28|, s92
	v_cmp_le_f32_e64 s[10:11], |v29|, s92
	v_fma_f32 v28, s38, -|v28|, v94
	v_fma_f32 v29, s38, -|v29|, v95
	v_cndmask_b32_e32 v28, v242, v28, vcc
	v_cndmask_b32_e64 v29, v242, v29, s[10:11]
	v_add_f32_e32 v30, 0x42680000, v32
	v_add_f32_e32 v31, 0x426c0000, v32
	v_cmp_le_f32_e64 vcc, |v30|, s92
	v_cmp_le_f32_e64 s[10:11], |v31|, s92
	v_fma_f32 v30, s38, -|v30|, v96
	v_fma_f32 v31, s38, -|v31|, v97
	v_cndmask_b32_e32 v30, v242, v30, vcc
	v_cndmask_b32_e64 v31, v242, v31, s[10:11]
	s_mov_b64 s[44:45], 0
.LBB0_906:
	s_andn2_b64 vcc, exec, s[44:45]
	s_cbranch_vccnz .LBB0_908
	v_fma_f32 v0, s38, -|v32|, v66
	v_add_f32_e32 v1, 1.0, v32
	v_add_f32_e32 v2, 2.0, v32
	v_add_f32_e32 v3, 0x40400000, v32
	v_add_f32_e32 v4, 0x41000000, v32
	v_add_f32_e32 v5, 0x41100000, v32
	v_add_f32_e32 v6, 0x41200000, v32
	v_add_f32_e32 v7, 0x41300000, v32
	v_add_f32_e32 v8, 0x41800000, v32
	v_add_f32_e32 v9, 0x41880000, v32
	v_add_f32_e32 v10, 0x41900000, v32
	v_add_f32_e32 v11, 0x41980000, v32
	v_add_f32_e32 v12, 0x41c00000, v32
	v_add_f32_e32 v13, 0x41c80000, v32
	v_add_f32_e32 v14, 0x41d00000, v32
	v_add_f32_e32 v15, 0x41d80000, v32
	v_add_f32_e32 v16, 0x42000000, v32
	v_add_f32_e32 v17, 0x42040000, v32
	v_add_f32_e32 v18, 0x42080000, v32
	v_add_f32_e32 v19, 0x420c0000, v32
	v_add_f32_e32 v20, 0x42200000, v32
	v_add_f32_e32 v21, 0x42240000, v32
	v_add_f32_e32 v22, 0x42280000, v32
	v_add_f32_e32 v23, 0x422c0000, v32
	v_add_f32_e32 v24, 0x42400000, v32
	v_add_f32_e32 v25, 0x42440000, v32
	v_add_f32_e32 v26, 0x42480000, v32
	v_add_f32_e32 v27, 0x424c0000, v32
	v_add_f32_e32 v28, 0x42600000, v32
	v_add_f32_e32 v29, 0x42640000, v32
	v_add_f32_e32 v30, 0x42680000, v32
	v_add_f32_e32 v31, 0x426c0000, v32
	v_fma_f32 v1, s38, -|v1|, v67
	v_fma_f32 v2, s38, -|v2|, v68
	v_fma_f32 v3, s38, -|v3|, v69
	v_fma_f32 v4, s38, -|v4|, v70
	v_fma_f32 v5, s38, -|v5|, v71
	v_fma_f32 v6, s38, -|v6|, v72
	v_fma_f32 v7, s38, -|v7|, v73
	v_fma_f32 v8, s38, -|v8|, v74
	v_fma_f32 v9, s38, -|v9|, v75
	v_fma_f32 v10, s38, -|v10|, v76
	v_fma_f32 v11, s38, -|v11|, v77
	v_fma_f32 v12, s38, -|v12|, v78
	v_fma_f32 v13, s38, -|v13|, v79
	v_fma_f32 v14, s38, -|v14|, v80
	v_fma_f32 v15, s38, -|v15|, v81
	v_fma_f32 v16, s38, -|v16|, v82
	v_fma_f32 v17, s38, -|v17|, v83
	v_fma_f32 v18, s38, -|v18|, v84
	v_fma_f32 v19, s38, -|v19|, v85
	v_fma_f32 v20, s38, -|v20|, v86
	v_fma_f32 v21, s38, -|v21|, v87
	v_fma_f32 v22, s38, -|v22|, v88
	v_fma_f32 v23, s38, -|v23|, v89
	v_fma_f32 v24, s38, -|v24|, v90
	v_fma_f32 v25, s38, -|v25|, v91
	v_fma_f32 v26, s38, -|v26|, v92
	v_fma_f32 v27, s38, -|v27|, v93
	v_fma_f32 v28, s38, -|v28|, v94
	v_fma_f32 v29, s38, -|v29|, v95
	v_fma_f32 v30, s38, -|v30|, v96
	v_fma_f32 v31, s38, -|v31|, v97

.LBB0_919:
	s_waitcnt vmcnt(0)
	v_mfma_f32_32x32x16_bf16 v[66:81], v[142:145], v[98:101], 0
	s_mov_b32 s16, s44
	s_add_i32 s44, s44, 1
	s_cmp_ge_u32 s44, s5
	v_lshl_add_u64 v[0:1], v[202:203], 0, s[48:49]
	s_cselect_b64 s[50:51], -1, 0
	s_cmp_lt_u32 s44, s5
	global_load_dwordx4 v[174:177], v[0:1], off
	global_load_dwordx4 v[170:173], v[0:1], off offset:1024
	global_load_dwordx4 v[166:169], v[0:1], off offset:2048
	global_load_dwordx4 v[162:165], v[0:1], off offset:3072
	v_mfma_f32_32x32x16_bf16 v[82:97], v[126:129], v[98:101], 0
	v_add_co_u32_e32 v0, vcc, s79, v0
	s_cselect_b32 s16, s44, s16
	s_nop 0
	v_addc_co_u32_e32 v1, vcc, 0, v1, vcc
	s_lshl_b64 s[48:49], s[16:17], 13
	global_load_dwordx4 v[158:161], v[0:1], off
	global_load_dwordx4 v[154:157], v[0:1], off offset:1024
	global_load_dwordx4 v[150:153], v[0:1], off offset:2048
	global_load_dwordx4 v[146:149], v[0:1], off offset:3072
	v_mfma_f32_32x32x16_bf16 v[66:81], v[138:141], v[102:105], v[66:81]
	v_lshl_add_u64 v[0:1], v[184:185], 0, s[48:49]
	global_load_dwordx4 v[142:145], v[0:1], off
	global_load_dwordx4 v[138:141], v[0:1], off offset:1024
	s_cmp_le_u32 s33, s4
	s_cselect_b64 s[52:53], -1, 0
	s_cmp_gt_i32 s33, s6
	v_mfma_f32_32x32x16_bf16 v[82:97], v[122:125], v[102:105], v[82:97]
	v_mfma_f32_32x32x16_bf16 v[66:81], v[134:137], v[106:109], v[66:81]
	v_mfma_f32_32x32x16_bf16 v[82:97], v[118:121], v[106:109], v[82:97]
	v_mfma_f32_32x32x16_bf16 v[66:81], v[130:133], v[110:113], v[66:81]
	global_load_dwordx4 v[134:137], v[0:1], off offset:2048
	global_load_dwordx4 v[130:133], v[0:1], off offset:3072
	v_add_co_u32_e32 v0, vcc, s79, v0
	s_nop 1
	v_addc_co_u32_e32 v1, vcc, 0, v1, vcc
	global_load_dwordx4 v[126:129], v[0:1], off
	global_load_dwordx4 v[122:125], v[0:1], off offset:1024
	v_mfma_f32_32x32x16_bf16 v[82:97], v[114:117], v[110:113], v[82:97]
	global_load_dwordx4 v[118:121], v[0:1], off offset:2048
	global_load_dwordx4 v[114:117], v[0:1], off offset:3072
	v_add_u32_e32 v0, s33, v212
	v_cvt_f32_i32_e32 v206, v0
	s_cselect_b64 vcc, -1, 0
	s_and_b64 vcc, s[52:53], vcc
	s_mov_b64 s[52:53], -1
	v_add_f32_e32 v213, 1.0, v206
	s_and_b64 vcc, exec, vcc
	v_and_b32_e32 v204, 0x7fffffff, v206
	v_and_b32_e32 v205, 0x7fffffff, v213
	s_cbranch_vccnz .LBB0_921
	v_add_f32_e32 v1, 1.0, v206
	v_cmp_le_f32_e64 vcc, |v206|, s91
	v_cmp_le_f32_e64 s[52:53], |v1|, s91
	v_fma_f32 v0, s46, -|v206|, v66
	v_fma_f32 v1, s46, -|v1|, v67
	v_cndmask_b32_e32 v0, v242, v0, vcc
	v_cndmask_b32_e64 v1, v242, v1, s[52:53]
	v_add_f32_e32 v2, 2.0, v206
	v_add_f32_e32 v3, 0x40400000, v206
	v_cmp_le_f32_e64 vcc, |v2|, s91
	v_cmp_le_f32_e64 s[52:53], |v3|, s91
	v_fma_f32 v2, s46, -|v2|, v68
	v_fma_f32 v3, s46, -|v3|, v69
	v_cndmask_b32_e32 v2, v242, v2, vcc
	v_cndmask_b32_e64 v3, v242, v3, s[52:53]
	v_add_f32_e32 v4, 0x41000000, v206
	v_add_f32_e32 v5, 0x41100000, v206
	v_cmp_le_f32_e64 vcc, |v4|, s91
	v_cmp_le_f32_e64 s[52:53], |v5|, s91
	v_fma_f32 v4, s46, -|v4|, v70
	v_fma_f32 v5, s46, -|v5|, v71
	v_cndmask_b32_e32 v4, v242, v4, vcc
	v_cndmask_b32_e64 v5, v242, v5, s[52:53]
	v_add_f32_e32 v6, 0x41200000, v206
	v_add_f32_e32 v7, 0x41300000, v206
	v_cmp_le_f32_e64 vcc, |v6|, s91
	v_cmp_le_f32_e64 s[52:53], |v7|, s91
	v_fma_f32 v6, s46, -|v6|, v72
	v_fma_f32 v7, s46, -|v7|, v73
	v_cndmask_b32_e32 v6, v242, v6, vcc
	v_cndmask_b32_e64 v7, v242, v7, s[52:53]
	v_add_f32_e32 v8, 0x41800000, v206
	v_add_f32_e32 v9, 0x41880000, v206
	v_cmp_le_f32_e64 vcc, |v8|, s91
	v_cmp_le_f32_e64 s[52:53], |v9|, s91
	v_fma_f32 v8, s46, -|v8|, v74
	v_fma_f32 v9, s46, -|v9|, v75
	v_cndmask_b32_e32 v8, v242, v8, vcc
	v_cndmask_b32_e64 v9, v242, v9, s[52:53]
	v_add_f32_e32 v10, 0x41900000, v206
	v_add_f32_e32 v11, 0x41980000, v206
	v_cmp_le_f32_e64 vcc, |v10|, s91
	v_cmp_le_f32_e64 s[52:53], |v11|, s91
	v_fma_f32 v10, s46, -|v10|, v76
	v_fma_f32 v11, s46, -|v11|, v77
	v_cndmask_b32_e32 v10, v242, v10, vcc
	v_cndmask_b32_e64 v11, v242, v11, s[52:53]
	v_add_f32_e32 v12, 0x41c00000, v206
	v_add_f32_e32 v13, 0x41c80000, v206
	v_cmp_le_f32_e64 vcc, |v12|, s91
	v_cmp_le_f32_e64 s[52:53], |v13|, s91
	v_fma_f32 v12, s46, -|v12|, v78
	v_fma_f32 v13, s46, -|v13|, v79
	v_cndmask_b32_e32 v12, v242, v12, vcc
	v_cndmask_b32_e64 v13, v242, v13, s[52:53]
	v_add_f32_e32 v14, 0x41d00000, v206
	v_add_f32_e32 v15, 0x41d80000, v206
	v_cmp_le_f32_e64 vcc, |v14|, s91
	v_cmp_le_f32_e64 s[52:53], |v15|, s91
	v_fma_f32 v14, s46, -|v14|, v80
	v_fma_f32 v15, s46, -|v15|, v81
	v_cndmask_b32_e32 v14, v242, v14, vcc
	v_cndmask_b32_e64 v15, v242, v15, s[52:53]
	v_add_f32_e32 v16, 0x42000000, v206
	v_add_f32_e32 v17, 0x42040000, v206
	v_cmp_le_f32_e64 vcc, |v16|, s91
	v_cmp_le_f32_e64 s[52:53], |v17|, s91
	v_fma_f32 v16, s46, -|v16|, v82
	v_fma_f32 v17, s46, -|v17|, v83
	v_cndmask_b32_e32 v16, v242, v16, vcc
	v_cndmask_b32_e64 v17, v242, v17, s[52:53]
	v_add_f32_e32 v18, 0x42080000, v206
	v_add_f32_e32 v19, 0x420c0000, v206
	v_cmp_le_f32_e64 vcc, |v18|, s91
	v_cmp_le_f32_e64 s[52:53], |v19|, s91
	v_fma_f32 v18, s46, -|v18|, v84
	v_fma_f32 v19, s46, -|v19|, v85
	v_cndmask_b32_e32 v18, v242, v18, vcc
	v_cndmask_b32_e64 v19, v242, v19, s[52:53]
	v_add_f32_e32 v20, 0x42200000, v206
	v_add_f32_e32 v21, 0x42240000, v206
	v_cmp_le_f32_e64 vcc, |v20|, s91
	v_cmp_le_f32_e64 s[52:53], |v21|, s91
	v_fma_f32 v20, s46, -|v20|, v86
	v_fma_f32 v21, s46, -|v21|, v87
	v_cndmask_b32_e32 v20, v242, v20, vcc
	v_cndmask_b32_e64 v21, v242, v21, s[52:53]
	v_add_f32_e32 v22, 0x42280000, v206
	v_add_f32_e32 v23, 0x422c0000, v206
	v_cmp_le_f32_e64 vcc, |v22|, s91
	v_cmp_le_f32_e64 s[52:53], |v23|, s91
	v_fma_f32 v22, s46, -|v22|, v88
	v_fma_f32 v23, s46, -|v23|, v89
	v_cndmask_b32_e32 v22, v242, v22, vcc
	v_cndmask_b32_e64 v23, v242, v23, s[52:53]
	v_add_f32_e32 v24, 0x42400000, v206
	v_add_f32_e32 v25, 0x42440000, v206
	v_cmp_le_f32_e64 vcc, |v24|, s91
	v_cmp_le_f32_e64 s[52:53], |v25|, s91
	v_fma_f32 v24, s46, -|v24|, v90
	v_fma_f32 v25, s46, -|v25|, v91
	v_cndmask_b32_e32 v24, v242, v24, vcc
	v_cndmask_b32_e64 v25, v242, v25, s[52:53]
	v_add_f32_e32 v26, 0x42480000, v206
	v_add_f32_e32 v27, 0x424c0000, v206
	v_cmp_le_f32_e64 vcc, |v26|, s91
	v_cmp_le_f32_e64 s[52:53], |v27|, s91
	v_fma_f32 v26, s46, -|v26|, v92
	v_fma_f32 v27, s46, -|v27|, v93
	v_cndmask_b32_e32 v26, v242, v26, vcc
	v_cndmask_b32_e64 v27, v242, v27, s[52:53]
	v_add_f32_e32 v28, 0x42600000, v206
	v_add_f32_e32 v29, 0x42640000, v206
	v_cmp_le_f32_e64 vcc, |v28|, s91
	v_cmp_le_f32_e64 s[52:53], |v29|, s91
	v_fma_f32 v28, s46, -|v28|, v94
	v_fma_f32 v29, s46, -|v29|, v95
	v_cndmask_b32_e32 v28, v242, v28, vcc
	v_cndmask_b32_e64 v29, v242, v29, s[52:53]
	v_add_f32_e32 v30, 0x42680000, v206
	v_add_f32_e32 v31, 0x426c0000, v206
	v_cmp_le_f32_e64 vcc, |v30|, s91
	v_cmp_le_f32_e64 s[52:53], |v31|, s91
	v_fma_f32 v30, s46, -|v30|, v96
	v_fma_f32 v31, s46, -|v31|, v97
	v_cndmask_b32_e32 v30, v242, v30, vcc
	v_cndmask_b32_e64 v31, v242, v31, s[52:53]
	s_mov_b64 s[52:53], 0
.LBB0_921:
	s_andn2_b64 vcc, exec, s[52:53]
	s_cbranch_vccnz .LBB0_923
	v_fma_f32 v0, s46, -|v206|, v66
	v_add_f32_e32 v1, 1.0, v206
	v_add_f32_e32 v2, 2.0, v206
	v_add_f32_e32 v3, 0x40400000, v206
	v_add_f32_e32 v4, 0x41000000, v206
	v_add_f32_e32 v5, 0x41100000, v206
	v_add_f32_e32 v6, 0x41200000, v206
	v_add_f32_e32 v7, 0x41300000, v206
	v_add_f32_e32 v8, 0x41800000, v206
	v_add_f32_e32 v9, 0x41880000, v206
	v_add_f32_e32 v10, 0x41900000, v206
	v_add_f32_e32 v11, 0x41980000, v206
	v_add_f32_e32 v12, 0x41c00000, v206
	v_add_f32_e32 v13, 0x41c80000, v206
	v_add_f32_e32 v14, 0x41d00000, v206
	v_add_f32_e32 v15, 0x41d80000, v206
	v_add_f32_e32 v16, 0x42000000, v206
	v_add_f32_e32 v17, 0x42040000, v206
	v_add_f32_e32 v18, 0x42080000, v206
	v_add_f32_e32 v19, 0x420c0000, v206
	v_add_f32_e32 v20, 0x42200000, v206
	v_add_f32_e32 v21, 0x42240000, v206
	v_add_f32_e32 v22, 0x42280000, v206
	v_add_f32_e32 v23, 0x422c0000, v206
	v_add_f32_e32 v24, 0x42400000, v206
	v_add_f32_e32 v25, 0x42440000, v206
	v_add_f32_e32 v26, 0x42480000, v206
	v_add_f32_e32 v27, 0x424c0000, v206
	v_add_f32_e32 v28, 0x42600000, v206
	v_add_f32_e32 v29, 0x42640000, v206
	v_add_f32_e32 v30, 0x42680000, v206
	v_add_f32_e32 v31, 0x426c0000, v206
	v_fma_f32 v1, s46, -|v1|, v67
	v_fma_f32 v2, s46, -|v2|, v68
	v_fma_f32 v3, s46, -|v3|, v69
	v_fma_f32 v4, s46, -|v4|, v70
	v_fma_f32 v5, s46, -|v5|, v71
	v_fma_f32 v6, s46, -|v6|, v72
	v_fma_f32 v7, s46, -|v7|, v73
	v_fma_f32 v8, s46, -|v8|, v74
	v_fma_f32 v9, s46, -|v9|, v75
	v_fma_f32 v10, s46, -|v10|, v76
	v_fma_f32 v11, s46, -|v11|, v77
	v_fma_f32 v12, s46, -|v12|, v78
	v_fma_f32 v13, s46, -|v13|, v79
	v_fma_f32 v14, s46, -|v14|, v80
	v_fma_f32 v15, s46, -|v15|, v81
	v_fma_f32 v16, s46, -|v16|, v82
	v_fma_f32 v17, s46, -|v17|, v83
	v_fma_f32 v18, s46, -|v18|, v84
	v_fma_f32 v19, s46, -|v19|, v85
	v_fma_f32 v20, s46, -|v20|, v86
	v_fma_f32 v21, s46, -|v21|, v87
	v_fma_f32 v22, s46, -|v22|, v88
	v_fma_f32 v23, s46, -|v23|, v89
	v_fma_f32 v24, s46, -|v24|, v90
	v_fma_f32 v25, s46, -|v25|, v91
	v_fma_f32 v26, s46, -|v26|, v92
	v_fma_f32 v27, s46, -|v27|, v93
	v_fma_f32 v28, s46, -|v28|, v94
	v_fma_f32 v29, s46, -|v29|, v95
	v_fma_f32 v30, s46, -|v30|, v96
	v_fma_f32 v31, s46, -|v31|, v97
